# adds: prompt pre-pass 31-tap conv per token as 4 interleaved partial chains and interleaved DPP reductions (was one dependent chain with a hazard nop per tap)
# speedup vs baseline: 1.0037x; 1.0037x over previous
.LBB0_792:
	s_or_b64 exec, exec, s[38:39]
	v_pk_fma_f32 v[130:131], v[36:37], v[188:189], v[98:99]
	s_waitcnt lgkmcnt(3)
	v_lshlrev_b32_e32 v188, 16, v192
	v_pk_mul_f32 v[246:247], v[38:39], v[184:185]
	v_and_b32_e32 v189, 0xffff0000, v192
	v_pk_mul_f32 v[248:249], v[40:41], v[126:127]
	v_pk_mul_f32 v[250:251], v[42:43], v[32:33]
	v_pk_fma_f32 v[130:131], v[44:45], v[30:31], v[130:131]
	v_pk_fma_f32 v[246:247], v[46:47], v[28:29], v[246:247]
	v_pk_fma_f32 v[248:249], v[48:49], v[26:27], v[248:249]
	v_pk_fma_f32 v[250:251], v[50:51], v[134:135], v[250:251]
	v_pk_fma_f32 v[130:131], v[52:53], v[136:137], v[130:131]
	v_pk_fma_f32 v[246:247], v[54:55], v[138:139], v[246:247]
	v_pk_fma_f32 v[248:249], v[56:57], v[146:147], v[248:249]
	v_pk_fma_f32 v[250:251], v[58:59], v[148:149], v[250:251]
	v_pk_fma_f32 v[130:131], v[64:65], v[150:151], v[130:131]
	v_pk_fma_f32 v[246:247], v[66:67], v[152:153], v[246:247]
	v_pk_fma_f32 v[248:249], v[68:69], v[154:155], v[248:249]
	v_pk_fma_f32 v[250:251], v[60:61], v[156:157], v[250:251]
	v_pk_fma_f32 v[130:131], v[62:63], v[158:159], v[130:131]
	v_pk_fma_f32 v[246:247], v[70:71], v[160:161], v[246:247]
	v_pk_fma_f32 v[248:249], v[72:73], v[162:163], v[248:249]
	v_pk_fma_f32 v[250:251], v[74:75], v[164:165], v[250:251]
	v_pk_fma_f32 v[130:131], v[76:77], v[166:167], v[130:131]
	v_pk_fma_f32 v[246:247], v[78:79], v[168:169], v[246:247]
	v_pk_fma_f32 v[248:249], v[80:81], v[170:171], v[248:249]
	v_pk_fma_f32 v[250:251], v[82:83], v[172:173], v[250:251]
	v_pk_fma_f32 v[130:131], v[84:85], v[174:175], v[130:131]
	v_pk_fma_f32 v[246:247], v[86:87], v[176:177], v[246:247]
	v_pk_fma_f32 v[248:249], v[88:89], v[178:179], v[248:249]
	v_pk_fma_f32 v[250:251], v[90:91], v[180:181], v[250:251]
	v_pk_fma_f32 v[130:131], v[92:93], v[182:183], v[130:131]
	v_pk_fma_f32 v[246:247], v[94:95], v[186:187], v[246:247]
	v_pk_fma_f32 v[248:249], v[96:97], v[188:189], v[248:249]
	v_pk_add_f32 v[130:131], v[130:131], v[246:247]
	v_pk_add_f32 v[248:249], v[248:249], v[250:251]
	s_nop 0
	v_pk_add_f32 v[132:133], v[130:131], v[248:249]
	s_nop 0
	v_add_f32_e32 v245, v132, v133
	v_pk_mul_f32 v[250:251], v[132:133], v[132:133]
	s_nop 0
	v_add_f32_dpp v245, v245, v245 row_ror:8 row_mask:0xf bank_mask:0xf bound_ctrl:1
	v_add_f32_e32 v246, v250, v251
	s_nop 1
	v_add_f32_dpp v246, v246, v246 row_ror:8 row_mask:0xf bank_mask:0xf bound_ctrl:1
	v_add_f32_dpp v245, v245, v245 row_ror:4 row_mask:0xf bank_mask:0xf bound_ctrl:1
	s_nop 0
	v_add_f32_dpp v246, v246, v246 row_ror:4 row_mask:0xf bank_mask:0xf bound_ctrl:1
	v_add_f32_dpp v245, v245, v245 row_ror:2 row_mask:0xf bank_mask:0xf bound_ctrl:1
	s_nop 0
	v_add_f32_dpp v246, v246, v246 row_ror:2 row_mask:0xf bank_mask:0xf bound_ctrl:1
	v_add_f32_dpp v245, v245, v245 row_ror:1 row_mask:0xf bank_mask:0xf bound_ctrl:1
	s_nop 0
	v_add_f32_dpp v246, v246, v246 row_ror:1 row_mask:0xf bank_mask:0xf bound_ctrl:1
	v_readlane_b32 s18, v245, 0
	v_readlane_b32 s44, v245, 16
	v_readlane_b32 s19, v245, 32
	v_readlane_b32 s45, v245, 48
	v_readlane_b32 s46, v246, 0
	v_readlane_b32 s48, v246, 16
	v_readlane_b32 s47, v246, 32
	v_readlane_b32 s49, v246, 48
	s_and_saveexec_b64 s[38:39], s[34:35]
	s_cbranch_execz .LBB0_794
	v_mov_b32_e32 v130, s48
	v_mov_b32_e32 v131, s49
	v_add_f32_e32 v130, s46, v130
	v_add_f32_e32 v131, s47, v131
	v_add_f32_e32 v130, v130, v131
	v_mov_b32_e32 v131, s44
	v_mov_b32_e32 v192, s45
	v_add_f32_e32 v131, s18, v131
	v_add_f32_e32 v192, s19, v192
	s_add_i32 s18, s85, s95
	v_add_f32_e32 v131, v131, v192
	v_mov_b32_e32 v192, s18
	ds_write2_b32 v192, v131, v130 offset0:1 offset1:9
.LBB0_794:
	s_or_b64 exec, exec, s[38:39]
	v_pk_fma_f32 v[130:131], v[36:37], v[184:185], v[98:99]
	s_waitcnt lgkmcnt(2)
	v_lshlrev_b32_e32 v184, 16, v190
	v_pk_mul_f32 v[246:247], v[38:39], v[126:127]
	v_and_b32_e32 v185, 0xffff0000, v190
	v_pk_mul_f32 v[248:249], v[40:41], v[32:33]
	v_pk_mul_f32 v[250:251], v[42:43], v[30:31]
	v_pk_fma_f32 v[130:131], v[44:45], v[28:29], v[130:131]
	v_pk_fma_f32 v[246:247], v[46:47], v[26:27], v[246:247]
	v_pk_fma_f32 v[248:249], v[48:49], v[134:135], v[248:249]
	v_pk_fma_f32 v[250:251], v[50:51], v[136:137], v[250:251]
	v_pk_fma_f32 v[130:131], v[52:53], v[138:139], v[130:131]
	v_pk_fma_f32 v[246:247], v[54:55], v[146:147], v[246:247]
	v_pk_fma_f32 v[248:249], v[56:57], v[148:149], v[248:249]
	v_pk_fma_f32 v[250:251], v[58:59], v[150:151], v[250:251]
	v_pk_fma_f32 v[130:131], v[64:65], v[152:153], v[130:131]
	v_pk_fma_f32 v[246:247], v[66:67], v[154:155], v[246:247]
	v_pk_fma_f32 v[248:249], v[68:69], v[156:157], v[248:249]
	v_pk_fma_f32 v[250:251], v[60:61], v[158:159], v[250:251]
	v_pk_fma_f32 v[130:131], v[62:63], v[160:161], v[130:131]
	v_pk_fma_f32 v[246:247], v[70:71], v[162:163], v[246:247]
	v_pk_fma_f32 v[248:249], v[72:73], v[164:165], v[248:249]
	v_pk_fma_f32 v[250:251], v[74:75], v[166:167], v[250:251]
	v_pk_fma_f32 v[130:131], v[76:77], v[168:169], v[130:131]
	v_pk_fma_f32 v[246:247], v[78:79], v[170:171], v[246:247]
	v_pk_fma_f32 v[248:249], v[80:81], v[172:173], v[248:249]
	v_pk_fma_f32 v[250:251], v[82:83], v[174:175], v[250:251]
	v_pk_fma_f32 v[130:131], v[84:85], v[176:177], v[130:131]
	v_pk_fma_f32 v[246:247], v[86:87], v[178:179], v[246:247]
	v_pk_fma_f32 v[248:249], v[88:89], v[180:181], v[248:249]
	v_pk_fma_f32 v[250:251], v[90:91], v[182:183], v[250:251]
	v_pk_fma_f32 v[130:131], v[92:93], v[186:187], v[130:131]
	v_pk_fma_f32 v[246:247], v[94:95], v[188:189], v[246:247]
	v_pk_fma_f32 v[248:249], v[96:97], v[184:185], v[248:249]
	v_pk_add_f32 v[130:131], v[130:131], v[246:247]
	v_pk_add_f32 v[248:249], v[248:249], v[250:251]
	s_nop 0
	v_pk_add_f32 v[130:131], v[130:131], v[248:249]
	s_nop 0
	v_add_f32_e32 v245, v130, v131
	v_pk_mul_f32 v[250:251], v[130:131], v[130:131]
	s_nop 0
	v_add_f32_dpp v245, v245, v245 row_ror:8 row_mask:0xf bank_mask:0xf bound_ctrl:1
	v_add_f32_e32 v246, v250, v251
	s_nop 1
	v_add_f32_dpp v246, v246, v246 row_ror:8 row_mask:0xf bank_mask:0xf bound_ctrl:1
	v_add_f32_dpp v245, v245, v245 row_ror:4 row_mask:0xf bank_mask:0xf bound_ctrl:1
	s_nop 0
	v_add_f32_dpp v246, v246, v246 row_ror:4 row_mask:0xf bank_mask:0xf bound_ctrl:1
	v_add_f32_dpp v245, v245, v245 row_ror:2 row_mask:0xf bank_mask:0xf bound_ctrl:1
	s_nop 0
	v_add_f32_dpp v246, v246, v246 row_ror:2 row_mask:0xf bank_mask:0xf bound_ctrl:1
	v_add_f32_dpp v245, v245, v245 row_ror:1 row_mask:0xf bank_mask:0xf bound_ctrl:1
	s_nop 0
	v_add_f32_dpp v246, v246, v246 row_ror:1 row_mask:0xf bank_mask:0xf bound_ctrl:1
	v_readlane_b32 s18, v245, 0
	v_readlane_b32 s44, v245, 16
	v_readlane_b32 s19, v245, 32
	v_readlane_b32 s45, v245, 48
	v_readlane_b32 s46, v246, 0
	v_readlane_b32 s48, v246, 16
	v_readlane_b32 s47, v246, 32
	v_readlane_b32 s49, v246, 48
	s_and_saveexec_b64 s[38:39], s[34:35]
	s_cbranch_execz .LBB0_796
	v_mov_b32_e32 v190, s48
	v_mov_b32_e32 v192, s49
	v_add_f32_e32 v190, s46, v190
	v_add_f32_e32 v192, s47, v192
	v_add_f32_e32 v190, v190, v192
	v_mov_b32_e32 v192, s44
	v_mov_b32_e32 v193, s45
	v_add_f32_e32 v192, s18, v192
	v_add_f32_e32 v193, s19, v193
	s_add_i32 s18, s85, s95
	v_add_f32_e32 v192, v192, v193
	v_mov_b32_e32 v193, s18
	ds_write2_b32 v193, v192, v190 offset0:2 offset1:10
.LBB0_796:
	s_or_b64 exec, exec, s[38:39]
	v_pk_fma_f32 v[126:127], v[36:37], v[126:127], v[98:99]
	v_lshlrev_b32_e32 v190, 16, v191
	v_pk_mul_f32 v[246:247], v[38:39], v[32:33]
	v_and_b32_e32 v191, 0xffff0000, v191
	v_pk_mul_f32 v[248:249], v[40:41], v[30:31]
	v_pk_mul_f32 v[250:251], v[42:43], v[28:29]
	v_pk_fma_f32 v[126:127], v[44:45], v[26:27], v[126:127]
	v_pk_fma_f32 v[246:247], v[46:47], v[134:135], v[246:247]
	v_pk_fma_f32 v[248:249], v[48:49], v[136:137], v[248:249]
	v_pk_fma_f32 v[250:251], v[50:51], v[138:139], v[250:251]
	v_pk_fma_f32 v[126:127], v[52:53], v[146:147], v[126:127]
	v_pk_fma_f32 v[246:247], v[54:55], v[148:149], v[246:247]
	v_pk_fma_f32 v[248:249], v[56:57], v[150:151], v[248:249]
	v_pk_fma_f32 v[250:251], v[58:59], v[152:153], v[250:251]
	v_pk_fma_f32 v[126:127], v[64:65], v[154:155], v[126:127]
	v_pk_fma_f32 v[246:247], v[66:67], v[156:157], v[246:247]
	v_pk_fma_f32 v[248:249], v[68:69], v[158:159], v[248:249]
	v_pk_fma_f32 v[250:251], v[60:61], v[160:161], v[250:251]
	v_pk_fma_f32 v[126:127], v[62:63], v[162:163], v[126:127]
	v_pk_fma_f32 v[246:247], v[70:71], v[164:165], v[246:247]
	v_pk_fma_f32 v[248:249], v[72:73], v[166:167], v[248:249]
	v_pk_fma_f32 v[250:251], v[74:75], v[168:169], v[250:251]
	v_pk_fma_f32 v[126:127], v[76:77], v[170:171], v[126:127]
	v_pk_fma_f32 v[246:247], v[78:79], v[172:173], v[246:247]
	v_pk_fma_f32 v[248:249], v[80:81], v[174:175], v[248:249]
	v_pk_fma_f32 v[250:251], v[82:83], v[176:177], v[250:251]
	v_pk_fma_f32 v[126:127], v[84:85], v[178:179], v[126:127]
	v_pk_fma_f32 v[246:247], v[86:87], v[180:181], v[246:247]
	v_pk_fma_f32 v[248:249], v[88:89], v[182:183], v[248:249]
	v_pk_fma_f32 v[250:251], v[90:91], v[186:187], v[250:251]
	v_pk_fma_f32 v[126:127], v[92:93], v[188:189], v[126:127]
	v_pk_fma_f32 v[246:247], v[94:95], v[184:185], v[246:247]
	v_pk_fma_f32 v[248:249], v[96:97], v[190:191], v[248:249]
	v_pk_add_f32 v[126:127], v[126:127], v[246:247]
	v_pk_add_f32 v[248:249], v[248:249], v[250:251]
	s_nop 0
	v_pk_add_f32 v[126:127], v[126:127], v[248:249]
	s_nop 0
	v_add_f32_e32 v245, v126, v127
	v_pk_mul_f32 v[250:251], v[126:127], v[126:127]
	s_nop 0
	v_add_f32_dpp v245, v245, v245 row_ror:8 row_mask:0xf bank_mask:0xf bound_ctrl:1
	v_add_f32_e32 v246, v250, v251
	s_nop 1
	v_add_f32_dpp v246, v246, v246 row_ror:8 row_mask:0xf bank_mask:0xf bound_ctrl:1
	v_add_f32_dpp v245, v245, v245 row_ror:4 row_mask:0xf bank_mask:0xf bound_ctrl:1
	s_nop 0
	v_add_f32_dpp v246, v246, v246 row_ror:4 row_mask:0xf bank_mask:0xf bound_ctrl:1
	v_add_f32_dpp v245, v245, v245 row_ror:2 row_mask:0xf bank_mask:0xf bound_ctrl:1
	s_nop 0
	v_add_f32_dpp v246, v246, v246 row_ror:2 row_mask:0xf bank_mask:0xf bound_ctrl:1
	v_add_f32_dpp v245, v245, v245 row_ror:1 row_mask:0xf bank_mask:0xf bound_ctrl:1
	s_nop 0
	v_add_f32_dpp v246, v246, v246 row_ror:1 row_mask:0xf bank_mask:0xf bound_ctrl:1
	v_readlane_b32 s18, v245, 0
	v_readlane_b32 s44, v245, 16
	v_readlane_b32 s19, v245, 32
	v_readlane_b32 s45, v245, 48
	v_readlane_b32 s46, v246, 0
	v_readlane_b32 s48, v246, 16
	v_readlane_b32 s47, v246, 32
	v_readlane_b32 s49, v246, 48
	s_and_saveexec_b64 s[38:39], s[34:35]
	s_cbranch_execz .LBB0_798
	v_mov_b32_e32 v192, s48
	v_mov_b32_e32 v193, s49
	v_add_f32_e32 v192, s46, v192
	v_add_f32_e32 v193, s47, v193
	v_add_f32_e32 v192, v192, v193
	v_mov_b32_e32 v193, s44
	v_mov_b32_e32 v200, s45
	v_add_f32_e32 v193, s18, v193
	v_add_f32_e32 v200, s19, v200
	s_add_i32 s18, s85, s95
	v_add_f32_e32 v193, v193, v200
	v_mov_b32_e32 v200, s18
	ds_write2_b32 v200, v193, v192 offset0:3 offset1:11
.LBB0_798:
	s_or_b64 exec, exec, s[38:39]
	v_pk_fma_f32 v[32:33], v[36:37], v[32:33], v[98:99]
	s_waitcnt lgkmcnt(1)
	v_lshlrev_b32_e32 v192, 16, v144
	v_pk_mul_f32 v[246:247], v[38:39], v[30:31]
	v_and_b32_e32 v193, 0xffff0000, v144
	v_pk_mul_f32 v[248:249], v[40:41], v[28:29]
	v_pk_mul_f32 v[250:251], v[42:43], v[26:27]
	v_pk_fma_f32 v[32:33], v[44:45], v[134:135], v[32:33]
	v_pk_fma_f32 v[246:247], v[46:47], v[136:137], v[246:247]
	v_pk_fma_f32 v[248:249], v[48:49], v[138:139], v[248:249]
	v_pk_fma_f32 v[250:251], v[50:51], v[146:147], v[250:251]
	v_pk_fma_f32 v[32:33], v[52:53], v[148:149], v[32:33]
	v_pk_fma_f32 v[246:247], v[54:55], v[150:151], v[246:247]
	v_pk_fma_f32 v[248:249], v[56:57], v[152:153], v[248:249]
	v_pk_fma_f32 v[250:251], v[58:59], v[154:155], v[250:251]
	v_pk_fma_f32 v[32:33], v[64:65], v[156:157], v[32:33]
	v_pk_fma_f32 v[246:247], v[66:67], v[158:159], v[246:247]
	v_pk_fma_f32 v[248:249], v[68:69], v[160:161], v[248:249]
	v_pk_fma_f32 v[250:251], v[60:61], v[162:163], v[250:251]
	v_pk_fma_f32 v[32:33], v[62:63], v[164:165], v[32:33]
	v_pk_fma_f32 v[246:247], v[70:71], v[166:167], v[246:247]
	v_pk_fma_f32 v[248:249], v[72:73], v[168:169], v[248:249]
	v_pk_fma_f32 v[250:251], v[74:75], v[170:171], v[250:251]
	v_pk_fma_f32 v[32:33], v[76:77], v[172:173], v[32:33]
	v_pk_fma_f32 v[246:247], v[78:79], v[174:175], v[246:247]
	v_pk_fma_f32 v[248:249], v[80:81], v[176:177], v[248:249]
	v_pk_fma_f32 v[250:251], v[82:83], v[178:179], v[250:251]
	v_pk_fma_f32 v[32:33], v[84:85], v[180:181], v[32:33]
	v_pk_fma_f32 v[246:247], v[86:87], v[182:183], v[246:247]
	v_pk_fma_f32 v[248:249], v[88:89], v[186:187], v[248:249]
	v_pk_fma_f32 v[250:251], v[90:91], v[188:189], v[250:251]
	v_pk_fma_f32 v[32:33], v[92:93], v[184:185], v[32:33]
	v_pk_fma_f32 v[246:247], v[94:95], v[190:191], v[246:247]
	v_pk_fma_f32 v[248:249], v[96:97], v[192:193], v[248:249]
	v_pk_add_f32 v[32:33], v[32:33], v[246:247]
	v_pk_add_f32 v[248:249], v[248:249], v[250:251]
	s_nop 0
	v_pk_add_f32 v[32:33], v[32:33], v[248:249]
	s_nop 0
	v_add_f32_e32 v245, v32, v33
	v_pk_mul_f32 v[250:251], v[32:33], v[32:33]
	s_nop 0
	v_add_f32_dpp v245, v245, v245 row_ror:8 row_mask:0xf bank_mask:0xf bound_ctrl:1
	v_add_f32_e32 v246, v250, v251
	s_nop 1
	v_add_f32_dpp v246, v246, v246 row_ror:8 row_mask:0xf bank_mask:0xf bound_ctrl:1
	v_add_f32_dpp v245, v245, v245 row_ror:4 row_mask:0xf bank_mask:0xf bound_ctrl:1
	s_nop 0
	v_add_f32_dpp v246, v246, v246 row_ror:4 row_mask:0xf bank_mask:0xf bound_ctrl:1
	v_add_f32_dpp v245, v245, v245 row_ror:2 row_mask:0xf bank_mask:0xf bound_ctrl:1
	s_nop 0
	v_add_f32_dpp v246, v246, v246 row_ror:2 row_mask:0xf bank_mask:0xf bound_ctrl:1
	v_add_f32_dpp v245, v245, v245 row_ror:1 row_mask:0xf bank_mask:0xf bound_ctrl:1
	s_nop 0
	v_add_f32_dpp v246, v246, v246 row_ror:1 row_mask:0xf bank_mask:0xf bound_ctrl:1
	v_readlane_b32 s18, v245, 0
	v_readlane_b32 s44, v245, 16
	v_readlane_b32 s19, v245, 32
	v_readlane_b32 s45, v245, 48
	v_readlane_b32 s46, v246, 0
	v_readlane_b32 s48, v246, 16
	v_readlane_b32 s47, v246, 32
	v_readlane_b32 s49, v246, 48
	s_and_saveexec_b64 s[38:39], s[34:35]
	s_cbranch_execz .LBB0_800
	v_mov_b32_e32 v144, s48
	v_mov_b32_e32 v200, s49
	v_add_f32_e32 v144, s46, v144
	v_add_f32_e32 v200, s47, v200
	v_add_f32_e32 v144, v144, v200
	v_mov_b32_e32 v200, s44
	v_mov_b32_e32 v201, s45
	v_add_f32_e32 v200, s18, v200
	v_add_f32_e32 v201, s19, v201
	s_add_i32 s18, s85, s95
	v_add_f32_e32 v200, v200, v201
	v_mov_b32_e32 v201, s18
	ds_write2_b32 v201, v200, v144 offset0:4 offset1:12
.LBB0_800:
	s_or_b64 exec, exec, s[38:39]
	v_pk_fma_f32 v[30:31], v[36:37], v[30:31], v[98:99]
	v_lshlrev_b32_e32 v144, 16, v145
	v_pk_mul_f32 v[246:247], v[38:39], v[28:29]
	v_and_b32_e32 v145, 0xffff0000, v145
	v_pk_mul_f32 v[248:249], v[40:41], v[26:27]
	v_pk_mul_f32 v[250:251], v[42:43], v[134:135]
	v_pk_fma_f32 v[30:31], v[44:45], v[136:137], v[30:31]
	v_pk_fma_f32 v[246:247], v[46:47], v[138:139], v[246:247]
	v_pk_fma_f32 v[248:249], v[48:49], v[146:147], v[248:249]
	v_pk_fma_f32 v[250:251], v[50:51], v[148:149], v[250:251]
	v_pk_fma_f32 v[30:31], v[52:53], v[150:151], v[30:31]
	v_pk_fma_f32 v[246:247], v[54:55], v[152:153], v[246:247]
	v_pk_fma_f32 v[248:249], v[56:57], v[154:155], v[248:249]
	v_pk_fma_f32 v[250:251], v[58:59], v[156:157], v[250:251]
	v_pk_fma_f32 v[30:31], v[64:65], v[158:159], v[30:31]
	v_pk_fma_f32 v[246:247], v[66:67], v[160:161], v[246:247]
	v_pk_fma_f32 v[248:249], v[68:69], v[162:163], v[248:249]
	v_pk_fma_f32 v[250:251], v[60:61], v[164:165], v[250:251]
	v_pk_fma_f32 v[30:31], v[62:63], v[166:167], v[30:31]
	v_pk_fma_f32 v[246:247], v[70:71], v[168:169], v[246:247]
	v_pk_fma_f32 v[248:249], v[72:73], v[170:171], v[248:249]
	v_pk_fma_f32 v[250:251], v[74:75], v[172:173], v[250:251]
	v_pk_fma_f32 v[30:31], v[76:77], v[174:175], v[30:31]
	v_pk_fma_f32 v[246:247], v[78:79], v[176:177], v[246:247]
	v_pk_fma_f32 v[248:249], v[80:81], v[178:179], v[248:249]
	v_pk_fma_f32 v[250:251], v[82:83], v[180:181], v[250:251]
	v_pk_fma_f32 v[30:31], v[84:85], v[182:183], v[30:31]
	v_pk_fma_f32 v[246:247], v[86:87], v[186:187], v[246:247]
	v_pk_fma_f32 v[248:249], v[88:89], v[188:189], v[248:249]
	v_pk_fma_f32 v[250:251], v[90:91], v[184:185], v[250:251]
	v_pk_fma_f32 v[30:31], v[92:93], v[190:191], v[30:31]
	v_pk_fma_f32 v[246:247], v[94:95], v[192:193], v[246:247]
	v_pk_fma_f32 v[248:249], v[96:97], v[144:145], v[248:249]
	v_pk_add_f32 v[30:31], v[30:31], v[246:247]
	v_pk_add_f32 v[248:249], v[248:249], v[250:251]
	s_nop 0
	v_pk_add_f32 v[30:31], v[30:31], v[248:249]
	s_nop 0
	v_add_f32_e32 v245, v30, v31
	v_pk_mul_f32 v[250:251], v[30:31], v[30:31]
	s_nop 0
	v_add_f32_dpp v245, v245, v245 row_ror:8 row_mask:0xf bank_mask:0xf bound_ctrl:1
	v_add_f32_e32 v246, v250, v251
	s_nop 1
	v_add_f32_dpp v246, v246, v246 row_ror:8 row_mask:0xf bank_mask:0xf bound_ctrl:1
	v_add_f32_dpp v245, v245, v245 row_ror:4 row_mask:0xf bank_mask:0xf bound_ctrl:1
	s_nop 0
	v_add_f32_dpp v246, v246, v246 row_ror:4 row_mask:0xf bank_mask:0xf bound_ctrl:1
	v_add_f32_dpp v245, v245, v245 row_ror:2 row_mask:0xf bank_mask:0xf bound_ctrl:1
	s_nop 0
	v_add_f32_dpp v246, v246, v246 row_ror:2 row_mask:0xf bank_mask:0xf bound_ctrl:1
	v_add_f32_dpp v245, v245, v245 row_ror:1 row_mask:0xf bank_mask:0xf bound_ctrl:1
	s_nop 0
	v_add_f32_dpp v246, v246, v246 row_ror:1 row_mask:0xf bank_mask:0xf bound_ctrl:1
	v_readlane_b32 s18, v245, 0
	v_readlane_b32 s44, v245, 16
	v_readlane_b32 s19, v245, 32
	v_readlane_b32 s45, v245, 48
	v_readlane_b32 s46, v246, 0
	v_readlane_b32 s48, v246, 16
	v_readlane_b32 s47, v246, 32
	v_readlane_b32 s49, v246, 48
	s_and_saveexec_b64 s[38:39], s[34:35]
	s_cbranch_execz .LBB0_802
	v_mov_b32_e32 v200, s48
	v_mov_b32_e32 v201, s49
	v_add_f32_e32 v200, s46, v200
	v_add_f32_e32 v201, s47, v201
	v_add_f32_e32 v200, v200, v201
	v_mov_b32_e32 v201, s44
	v_mov_b32_e32 v204, s45
	v_add_f32_e32 v201, s18, v201
	v_add_f32_e32 v204, s19, v204
	s_add_i32 s18, s85, s95
	v_add_f32_e32 v201, v201, v204
	v_mov_b32_e32 v204, s18
	ds_write2_b32 v204, v201, v200 offset0:5 offset1:13
.LBB0_802:
	s_or_b64 exec, exec, s[38:39]
	v_pk_fma_f32 v[28:29], v[36:37], v[28:29], v[98:99]
	s_waitcnt lgkmcnt(0)
	v_lshlrev_b32_e32 v204, 16, v140
	v_pk_mul_f32 v[246:247], v[38:39], v[26:27]
	v_and_b32_e32 v205, 0xffff0000, v140
	v_pk_mul_f32 v[248:249], v[40:41], v[134:135]
	v_pk_mul_f32 v[250:251], v[42:43], v[136:137]
	v_pk_fma_f32 v[28:29], v[44:45], v[138:139], v[28:29]
	v_pk_fma_f32 v[246:247], v[46:47], v[146:147], v[246:247]
	v_pk_fma_f32 v[248:249], v[48:49], v[148:149], v[248:249]
	v_pk_fma_f32 v[250:251], v[50:51], v[150:151], v[250:251]
	v_pk_fma_f32 v[28:29], v[52:53], v[152:153], v[28:29]
	v_pk_fma_f32 v[246:247], v[54:55], v[154:155], v[246:247]
	v_pk_fma_f32 v[248:249], v[56:57], v[156:157], v[248:249]
	v_pk_fma_f32 v[250:251], v[58:59], v[158:159], v[250:251]
	v_pk_fma_f32 v[28:29], v[64:65], v[160:161], v[28:29]
	v_pk_fma_f32 v[246:247], v[66:67], v[162:163], v[246:247]
	v_pk_fma_f32 v[248:249], v[68:69], v[164:165], v[248:249]
	v_pk_fma_f32 v[250:251], v[60:61], v[166:167], v[250:251]
	v_pk_fma_f32 v[28:29], v[62:63], v[168:169], v[28:29]
	v_pk_fma_f32 v[246:247], v[70:71], v[170:171], v[246:247]
	v_pk_fma_f32 v[248:249], v[72:73], v[172:173], v[248:249]
	v_pk_fma_f32 v[250:251], v[74:75], v[174:175], v[250:251]
	v_pk_fma_f32 v[28:29], v[76:77], v[176:177], v[28:29]
	v_pk_fma_f32 v[246:247], v[78:79], v[178:179], v[246:247]
	v_pk_fma_f32 v[248:249], v[80:81], v[180:181], v[248:249]
	v_pk_fma_f32 v[250:251], v[82:83], v[182:183], v[250:251]
	v_pk_fma_f32 v[28:29], v[84:85], v[186:187], v[28:29]
	v_pk_fma_f32 v[246:247], v[86:87], v[188:189], v[246:247]
	v_pk_fma_f32 v[248:249], v[88:89], v[184:185], v[248:249]
	v_pk_fma_f32 v[250:251], v[90:91], v[190:191], v[250:251]
	v_pk_fma_f32 v[28:29], v[92:93], v[192:193], v[28:29]
	v_pk_fma_f32 v[246:247], v[94:95], v[144:145], v[246:247]
	v_pk_fma_f32 v[248:249], v[96:97], v[204:205], v[248:249]
	v_pk_add_f32 v[28:29], v[28:29], v[246:247]
	v_pk_add_f32 v[248:249], v[248:249], v[250:251]
	s_nop 0
	v_pk_add_f32 v[28:29], v[28:29], v[248:249]
	s_nop 0
	v_add_f32_e32 v245, v28, v29
	v_pk_mul_f32 v[250:251], v[28:29], v[28:29]
	s_nop 0
	v_add_f32_dpp v245, v245, v245 row_ror:8 row_mask:0xf bank_mask:0xf bound_ctrl:1
	v_add_f32_e32 v246, v250, v251
	s_nop 1
	v_add_f32_dpp v246, v246, v246 row_ror:8 row_mask:0xf bank_mask:0xf bound_ctrl:1
	v_add_f32_dpp v245, v245, v245 row_ror:4 row_mask:0xf bank_mask:0xf bound_ctrl:1
	s_nop 0
	v_add_f32_dpp v246, v246, v246 row_ror:4 row_mask:0xf bank_mask:0xf bound_ctrl:1
	v_add_f32_dpp v245, v245, v245 row_ror:2 row_mask:0xf bank_mask:0xf bound_ctrl:1
	s_nop 0
	v_add_f32_dpp v246, v246, v246 row_ror:2 row_mask:0xf bank_mask:0xf bound_ctrl:1
	v_add_f32_dpp v245, v245, v245 row_ror:1 row_mask:0xf bank_mask:0xf bound_ctrl:1
	s_nop 0
	v_add_f32_dpp v246, v246, v246 row_ror:1 row_mask:0xf bank_mask:0xf bound_ctrl:1
	v_readlane_b32 s18, v245, 0
	v_readlane_b32 s44, v245, 16
	v_readlane_b32 s19, v245, 32
	v_readlane_b32 s45, v245, 48
	v_readlane_b32 s46, v246, 0
	v_readlane_b32 s48, v246, 16
	v_readlane_b32 s47, v246, 32
	v_readlane_b32 s49, v246, 48
	s_and_saveexec_b64 s[38:39], s[34:35]
	s_cbranch_execz .LBB0_804
	v_mov_b32_e32 v140, s48
	v_mov_b32_e32 v200, s49
	v_add_f32_e32 v140, s46, v140
	v_add_f32_e32 v200, s47, v200
	v_add_f32_e32 v140, v140, v200
	v_mov_b32_e32 v200, s44
	v_mov_b32_e32 v201, s45
	v_add_f32_e32 v200, s18, v200
	v_add_f32_e32 v201, s19, v201
	s_add_i32 s18, s85, s95
	v_add_f32_e32 v200, v200, v201
	v_mov_b32_e32 v201, s18
	ds_write2_b32 v201, v200, v140 offset0:6 offset1:14
.LBB0_804:
	s_or_b64 exec, exec, s[38:39]
	v_pk_fma_f32 v[26:27], v[36:37], v[26:27], v[98:99]
	v_pk_mul_f32 v[246:247], v[38:39], v[134:135]
	v_lshlrev_b32_e32 v134, 16, v141
	v_pk_mul_f32 v[248:249], v[40:41], v[136:137]
	v_and_b32_e32 v135, 0xffff0000, v141
	v_pk_mul_f32 v[250:251], v[42:43], v[138:139]
	v_pk_fma_f32 v[26:27], v[44:45], v[146:147], v[26:27]
	v_pk_fma_f32 v[246:247], v[46:47], v[148:149], v[246:247]
	v_pk_fma_f32 v[248:249], v[48:49], v[150:151], v[248:249]
	v_pk_fma_f32 v[250:251], v[50:51], v[152:153], v[250:251]
	v_pk_fma_f32 v[26:27], v[52:53], v[154:155], v[26:27]
	v_pk_fma_f32 v[246:247], v[54:55], v[156:157], v[246:247]
	v_pk_fma_f32 v[248:249], v[56:57], v[158:159], v[248:249]
	v_pk_fma_f32 v[250:251], v[58:59], v[160:161], v[250:251]
	v_pk_fma_f32 v[26:27], v[64:65], v[162:163], v[26:27]
	v_pk_fma_f32 v[246:247], v[66:67], v[164:165], v[246:247]
	v_pk_fma_f32 v[248:249], v[68:69], v[166:167], v[248:249]
	v_pk_fma_f32 v[250:251], v[60:61], v[168:169], v[250:251]
	v_pk_fma_f32 v[26:27], v[62:63], v[170:171], v[26:27]
	v_pk_fma_f32 v[246:247], v[70:71], v[172:173], v[246:247]
	v_pk_fma_f32 v[248:249], v[72:73], v[174:175], v[248:249]
	v_pk_fma_f32 v[250:251], v[74:75], v[176:177], v[250:251]
	v_pk_fma_f32 v[26:27], v[76:77], v[178:179], v[26:27]
	v_pk_fma_f32 v[246:247], v[78:79], v[180:181], v[246:247]
	v_pk_fma_f32 v[248:249], v[80:81], v[182:183], v[248:249]
	v_pk_fma_f32 v[250:251], v[82:83], v[186:187], v[250:251]
	v_pk_fma_f32 v[26:27], v[84:85], v[188:189], v[26:27]
	v_pk_fma_f32 v[246:247], v[86:87], v[184:185], v[246:247]
	v_pk_fma_f32 v[248:249], v[88:89], v[190:191], v[248:249]
	v_pk_fma_f32 v[250:251], v[90:91], v[192:193], v[250:251]
	v_pk_fma_f32 v[26:27], v[92:93], v[144:145], v[26:27]
	v_pk_fma_f32 v[246:247], v[94:95], v[204:205], v[246:247]
	v_pk_fma_f32 v[248:249], v[96:97], v[134:135], v[248:249]
	v_pk_add_f32 v[26:27], v[26:27], v[246:247]
	v_pk_add_f32 v[248:249], v[248:249], v[250:251]
	s_nop 0
	v_pk_add_f32 v[26:27], v[26:27], v[248:249]
	s_nop 0
	v_add_f32_e32 v245, v26, v27
	v_pk_mul_f32 v[250:251], v[26:27], v[26:27]
	s_nop 0
	v_add_f32_dpp v245, v245, v245 row_ror:8 row_mask:0xf bank_mask:0xf bound_ctrl:1
	v_add_f32_e32 v246, v250, v251
	s_nop 1
	v_add_f32_dpp v246, v246, v246 row_ror:8 row_mask:0xf bank_mask:0xf bound_ctrl:1
	v_add_f32_dpp v245, v245, v245 row_ror:4 row_mask:0xf bank_mask:0xf bound_ctrl:1
	s_nop 0
	v_add_f32_dpp v246, v246, v246 row_ror:4 row_mask:0xf bank_mask:0xf bound_ctrl:1
	v_add_f32_dpp v245, v245, v245 row_ror:2 row_mask:0xf bank_mask:0xf bound_ctrl:1
	s_nop 0
	v_add_f32_dpp v246, v246, v246 row_ror:2 row_mask:0xf bank_mask:0xf bound_ctrl:1
	v_add_f32_dpp v245, v245, v245 row_ror:1 row_mask:0xf bank_mask:0xf bound_ctrl:1
	s_nop 0
	v_add_f32_dpp v246, v246, v246 row_ror:1 row_mask:0xf bank_mask:0xf bound_ctrl:1
	v_readlane_b32 s18, v245, 0
	v_readlane_b32 s44, v245, 16
	v_readlane_b32 s19, v245, 32
	v_readlane_b32 s45, v245, 48
	v_readlane_b32 s46, v246, 0
	v_readlane_b32 s48, v246, 16
	v_readlane_b32 s47, v246, 32
	v_readlane_b32 s49, v246, 48
	s_and_saveexec_b64 s[38:39], s[34:35]
	s_cbranch_execz .LBB0_806
	v_mov_b32_e32 v134, s48
	v_mov_b32_e32 v135, s49
	v_add_f32_e32 v134, s46, v134
	v_add_f32_e32 v135, s47, v135
	v_add_f32_e32 v134, v134, v135
	v_mov_b32_e32 v135, s44
	v_mov_b32_e32 v136, s45
	v_add_f32_e32 v135, s18, v135
	v_add_f32_e32 v136, s19, v136
	s_add_i32 s18, s85, s95
	v_add_f32_e32 v135, v135, v136
	v_mov_b32_e32 v136, s18
	ds_write2_b32 v136, v135, v134 offset0:7 offset1:15
